# adds the same MFMA-VALU interleave (slice-major PV, exp/sum/cvt groups in MFMA shadow) to the MLA attention tile loop
# baseline (speedup 1.0000x reference)
; #define LAS __attribute__((address_space(3)))
; __device__ __forceinline__ int crow(int r, int hi) { return (r & 3) + 8 * (r >> 2) + 4 * hi; }
; __device__ __forceinline__ s16x4 vtr(const LAS unsigned char* p) { return __builtin_bit_cast(s16x4, __builtin_amdgcn_ds_read_tr16_b64_v4i16((LAS v4i16_t*)p)); }
; template <int DQK, int DV, bool HAS_BIAS>
; __device__ __forceinline__ void attn_tile(AttnState<DQK, DV>& st, const LAS unsigned char* Kt, const LAS unsigned char* Vt, int bias_mode, const LAS float* tab, int rel0, int nkeys, bool first, LAS float* wsf, int lane) {
;     ...
;         p0 = __builtin_amdgcn_mfma_f32_32x32x16_bf16(ka[0], st.qf[0], p0, 0, 0, 0);
;         p1 = __builtin_amdgcn_mfma_f32_32x32x16_bf16(kb[0], st.qf[0], p1, 0, 0, 0);
;     } else {
;         p0 = __builtin_amdgcn_mfma_f32_32x32x16_bf16(ka[0], st.qf[0], st.negm, 0, 0, 0);
;         p1 = __builtin_amdgcn_mfma_f32_32x32x16_bf16(kb[0], st.qf[0], st.negm, 0, 0, 0);
;     }
; #pragma unroll
;     for (int ks = 1; ks < KS; ++ks) {
;         p0 = __builtin_amdgcn_mfma_f32_32x32x16_bf16(ka[ks], st.qf[ks], p0, 0, 0, 0);
;         p1 = __builtin_amdgcn_mfma_f32_32x32x16_bf16(kb[ks], st.qf[ks], p1, 0, 0, 0);
;     }
;     const int q4 = (lane & 15) >> 2, blk = (lane >> 4) & 1, pp = lane & 3;
;     const LAS unsigned char* vp = Vt + (4 * hi + q4) * PV + (16 * blk + 4 * pp) * 2;
;     s16x4 vlo[2][4], vhi[2][4];
; #pragma unroll
;     for (int s4 = 0; s4 < 4; ++s4) { vlo[0][s4] = vtr(vp + (16 * s4) * PV); vhi[0][s4] = vtr(vp + (16 * s4 + 8) * PV); }
;     __builtin_amdgcn_sched_barrier(0);
;     if (nkeys < 64) {
; #pragma unroll
;         for (int r = 0; r < 16; ++r) { const int k = crow(r, hi); if (k >= nkeys) p0[r] = -1e30f; if (k + 32 >= nkeys) p1[r] = -1e30f; }
;     }
;     float mxa = __builtin_fmaxf(__builtin_fmaxf(p0[0], p0[1]), p1[0]), mxb = __builtin_fmaxf(__builtin_fmaxf(p0[2], p0[3]), p1[1]);
;     mxa = __builtin_fmaxf(__builtin_fmaxf(mxa, p1[2]), p1[3]);
; #pragma unroll
;     for (int r = 4; r < 16; r += 4) {
;         mxa = __builtin_fmaxf(__builtin_fmaxf(mxa, p0[r]), p0[r + 1]); mxb = __builtin_fmaxf(__builtin_fmaxf(mxb, p0[r + 2]), p0[r + 3]);
;         mxa = __builtin_fmaxf(__builtin_fmaxf(mxa, p1[r]), p1[r + 1]); mxb = __builtin_fmaxf(__builtin_fmaxf(mxb, p1[r + 2]), p1[r + 3]);
;     }
;     const float mx = xmax32(__builtin_fmaxf(mxa, mxb));
.LBB0_580:
	ds_read_b128 v[64:67], v162 offset:8192
	ds_read_b128 v[128:131], v162 offset:8224
	ds_read_b128 v[132:135], v162 offset:14848
	ds_read_b128 v[136:139], v162 offset:14880
	s_cmp_eq_u32 s58, 0
	s_cselect_b64 s[4:5], -1, 0
	s_waitcnt lgkmcnt(3)
	v_mfma_f32_32x32x16_bf16 v[48:63], v[64:67], v[100:103], v[32:47]
	s_cmp_lg_u32 s58, 0
	s_waitcnt lgkmcnt(1)
	v_mfma_f32_32x32x16_bf16 v[64:79], v[132:135], v[100:103], v[32:47]
	v_mfma_f32_32x32x16_bf16 v[48:63], v[128:131], v[80:83], v[48:63]
	ds_read_b128 v[128:131], v162 offset:8256
	ds_read_b128 v[132:135], v162 offset:8288
	s_waitcnt lgkmcnt(2)
	v_mfma_f32_32x32x16_bf16 v[64:79], v[136:139], v[80:83], v[64:79]
	s_waitcnt lgkmcnt(1)
	v_mfma_f32_32x32x16_bf16 v[48:63], v[128:131], v[84:87], v[48:63]
	ds_read_b128 v[128:131], v162 offset:14912
	ds_read_b128 v[136:139], v162 offset:14944
	s_waitcnt lgkmcnt(1)
	v_mfma_f32_32x32x16_bf16 v[64:79], v[128:131], v[84:87], v[64:79]
	v_mfma_f32_32x32x16_bf16 v[48:63], v[132:135], v[88:91], v[48:63]
	ds_read_b128 v[128:131], v162 offset:8320
	ds_read_b128 v[132:135], v162 offset:8352
	s_waitcnt lgkmcnt(2)
	v_mfma_f32_32x32x16_bf16 v[64:79], v[136:139], v[88:91], v[64:79]
	s_waitcnt lgkmcnt(1)
	v_mfma_f32_32x32x16_bf16 v[48:63], v[128:131], v[92:95], v[48:63]
	ds_read_b128 v[128:131], v162 offset:14976
	ds_read_b128 v[164:167], v162 offset:15008
	s_waitcnt lgkmcnt(1)
	v_mfma_f32_32x32x16_bf16 v[64:79], v[128:131], v[92:95], v[64:79]
	v_mfma_f32_32x32x16_bf16 v[48:63], v[132:135], v[96:99], v[48:63]
	ds_read_b64_tr_b16 v[128:129], v163 offset:21504
	ds_read_b64_tr_b16 v[130:131], v163 offset:23040
	ds_read_b64_tr_b16 v[132:133], v163 offset:21568
	ds_read_b64_tr_b16 v[134:135], v163 offset:23104
	ds_read_b64_tr_b16 v[136:137], v163 offset:24576
	ds_read_b64_tr_b16 v[138:139], v163 offset:26112
	ds_read_b64_tr_b16 v[140:141], v163 offset:24640
	ds_read_b64_tr_b16 v[142:143], v163 offset:26176
	s_waitcnt lgkmcnt(8)
	v_mfma_f32_32x32x16_bf16 v[64:79], v[164:167], v[96:99], v[64:79]
	s_nop 1
	v_max_f32_e32 v152, v49, v49
	v_max_f32_e32 v164, v48, v48
	v_max_f32_e32 v152, v164, v152
	s_nop 6
	v_max3_f32 v164, v50, v51, v65
	v_max3_f32 v152, v152, v64, v66
	v_max3_f32 v152, v152, v67, v52
	v_max3_f32 v164, v164, v54, v55
	v_max3_f32 v152, v152, v53, v68
	v_max3_f32 v164, v164, v70, v71
	v_max3_f32 v152, v152, v69, v56
	v_max3_f32 v164, v164, v58, v59
	v_max3_f32 v152, v152, v57, v72
	v_max3_f32 v164, v164, v74, v75
	v_max3_f32 v152, v152, v73, v60
	v_max3_f32 v164, v164, v62, v63
	v_max3_f32 v152, v152, v61, v76
	v_max3_f32 v164, v164, v78, v79
	v_max3_f32 v152, v152, v77, v164
	v_mov_b32_e32 v164, v152
	s_nop 1
	v_permlane32_swap_b32_e32 v152, v164
	v_max_f32_e32 v164, v164, v164
	v_max_f32_e32 v152, v152, v152
	v_max_f32_e32 v152, v152, v164
	s_cbranch_scc0 .LBB0_595
	v_cmp_lt_f32_e32 vcc, s77, v152
	s_cmp_lg_u64 vcc, 0
	s_cselect_b64 s[38:39], -1, 0
	s_cbranch_execz .LBB0_596
	s_branch .LBB0_597

; template <int DQK, int DV, bool HAS_BIAS>
; __device__ __forceinline__ void attn_tile(AttnState<DQK, DV>& st, const LAS unsigned char* Kt, const LAS unsigned char* Vt, int bias_mode, const LAS float* tab, int rel0, int nkeys, bool first, LAS float* wsf, int lane) {
;     ...
;         p0 = __builtin_amdgcn_mfma_f32_32x32x16_bf16(ka[0], st.qf[0], p0, 0, 0, 0);
;         p1 = __builtin_amdgcn_mfma_f32_32x32x16_bf16(kb[0], st.qf[0], p1, 0, 0, 0);
;     } else {
;         p0 = __builtin_amdgcn_mfma_f32_32x32x16_bf16(ka[0], st.qf[0], st.negm, 0, 0, 0);
;         p1 = __builtin_amdgcn_mfma_f32_32x32x16_bf16(kb[0], st.qf[0], st.negm, 0, 0, 0);
;     }
; #pragma unroll
;     for (int ks = 1; ks < KS; ++ks) {
;         p0 = __builtin_amdgcn_mfma_f32_32x32x16_bf16(ka[ks], st.qf[ks], p0, 0, 0, 0);
;         p1 = __builtin_amdgcn_mfma_f32_32x32x16_bf16(kb[ks], st.qf[ks], p1, 0, 0, 0);
;     }
;     const int q4 = (lane & 15) >> 2, blk = (lane >> 4) & 1, pp = lane & 3;
;     const LAS unsigned char* vp = Vt + (4 * hi + q4) * PV + (16 * blk + 4 * pp) * 2;
;     s16x4 vlo[2][4], vhi[2][4];
; #pragma unroll
;     for (int s4 = 0; s4 < 4; ++s4) { vlo[0][s4] = vtr(vp + (16 * s4) * PV); vhi[0][s4] = vtr(vp + (16 * s4 + 8) * PV); }
;     __builtin_amdgcn_sched_barrier(0);
;     if (nkeys < 64) {
; #pragma unroll
;         for (int r = 0; r < 16; ++r) { const int k = crow(r, hi); if (k >= nkeys) p0[r] = -1e30f; if (k + 32 >= nkeys) p1[r] = -1e30f; }
;     }
;     float mxa = __builtin_fmaxf(__builtin_fmaxf(p0[0], p0[1]), p1[0]), mxb = __builtin_fmaxf(__builtin_fmaxf(p0[2], p0[3]), p1[1]);
;     mxa = __builtin_fmaxf(__builtin_fmaxf(mxa, p1[2]), p1[3]);
; #pragma unroll
;     for (int r = 4; r < 16; r += 4) {
;         mxa = __builtin_fmaxf(__builtin_fmaxf(mxa, p0[r]), p0[r + 1]); mxb = __builtin_fmaxf(__builtin_fmaxf(mxb, p0[r + 2]), p0[r + 3]);
;         mxa = __builtin_fmaxf(__builtin_fmaxf(mxa, p1[r]), p1[r + 1]); mxb = __builtin_fmaxf(__builtin_fmaxf(mxb, p1[r + 2]), p1[r + 3]);
;     }
;     const float mx = xmax32(__builtin_fmaxf(mxa, mxb));
;     if (first || __any(mx > ATT_THR)) {
;         const float dl = first ? mx : __builtin_fmaxf(mx, 0.f);
;         st.m += dl;
; #pragma unroll
;         for (int r = 0; r < 16; ++r) { st.negm[r] = -st.m; p0[r] -= dl; p1[r] -= dl; }
;         const float f = __builtin_amdgcn_exp2f(-dl);
;         st.l *= f;
.LBB0_585:
	ds_read_b128 v[64:67], v162 offset:33792
	ds_read_b128 v[128:131], v162 offset:33824
	ds_read_b128 v[132:135], v162 offset:40448
	ds_read_b128 v[136:139], v162 offset:40480
	s_waitcnt lgkmcnt(3)
	v_mfma_f32_32x32x16_bf16 v[48:63], v[64:67], v[100:103], v[32:47]
	s_waitcnt lgkmcnt(1)
	v_mfma_f32_32x32x16_bf16 v[64:79], v[132:135], v[100:103], v[32:47]
	v_mfma_f32_32x32x16_bf16 v[48:63], v[128:131], v[80:83], v[48:63]
	ds_read_b128 v[128:131], v162 offset:33856
	ds_read_b128 v[132:135], v162 offset:33888
	s_waitcnt lgkmcnt(2)
	v_mfma_f32_32x32x16_bf16 v[64:79], v[136:139], v[80:83], v[64:79]
	s_waitcnt lgkmcnt(1)
	v_mfma_f32_32x32x16_bf16 v[48:63], v[128:131], v[84:87], v[48:63]
	ds_read_b128 v[128:131], v162 offset:40512
	ds_read_b128 v[136:139], v162 offset:40544
	s_waitcnt lgkmcnt(1)
	v_mfma_f32_32x32x16_bf16 v[64:79], v[128:131], v[84:87], v[64:79]
	v_mfma_f32_32x32x16_bf16 v[48:63], v[132:135], v[88:91], v[48:63]
	ds_read_b128 v[128:131], v162 offset:33920
	ds_read_b128 v[132:135], v162 offset:33952
	s_waitcnt lgkmcnt(2)
	v_mfma_f32_32x32x16_bf16 v[64:79], v[136:139], v[88:91], v[64:79]
	s_waitcnt lgkmcnt(1)
	v_mfma_f32_32x32x16_bf16 v[48:63], v[128:131], v[92:95], v[48:63]
	ds_read_b128 v[128:131], v162 offset:40576
	ds_read_b128 v[164:167], v162 offset:40608
	s_waitcnt lgkmcnt(1)
	v_mfma_f32_32x32x16_bf16 v[64:79], v[128:131], v[92:95], v[64:79]
	v_mfma_f32_32x32x16_bf16 v[48:63], v[132:135], v[96:99], v[48:63]
	ds_read_b64_tr_b16 v[128:129], v163 offset:47104
	ds_read_b64_tr_b16 v[130:131], v163 offset:48640
	ds_read_b64_tr_b16 v[132:133], v163 offset:47168
	ds_read_b64_tr_b16 v[134:135], v163 offset:48704
	ds_read_b64_tr_b16 v[136:137], v163 offset:50176
	ds_read_b64_tr_b16 v[138:139], v163 offset:51712
	ds_read_b64_tr_b16 v[140:141], v163 offset:50240
	ds_read_b64_tr_b16 v[142:143], v163 offset:51776
	s_waitcnt lgkmcnt(8)
	v_mfma_f32_32x32x16_bf16 v[64:79], v[164:167], v[96:99], v[64:79]
	s_nop 1
	v_max_f32_e32 v150, v49, v49
	v_max_f32_e32 v151, v48, v48
	v_max_f32_e32 v150, v151, v150
	s_nop 6
	v_max3_f32 v151, v50, v51, v65
	v_max3_f32 v150, v150, v64, v66
	v_max3_f32 v150, v150, v67, v52
	v_max3_f32 v151, v151, v54, v55
	v_max3_f32 v150, v150, v53, v68
	v_max3_f32 v151, v151, v70, v71
	v_max3_f32 v150, v150, v69, v56
	v_max3_f32 v151, v151, v58, v59
	v_max3_f32 v150, v150, v57, v72
	v_max3_f32 v151, v151, v74, v75
	v_max3_f32 v150, v150, v73, v60
	v_max3_f32 v151, v151, v62, v63
	v_max3_f32 v150, v150, v61, v76
	v_max3_f32 v151, v151, v78, v79
	v_max3_f32 v150, v150, v77, v151
	v_mov_b32_e32 v151, v150
	s_nop 1
	v_permlane32_swap_b32_e32 v150, v151
	v_max_f32_e32 v151, v151, v151
	v_max_f32_e32 v150, v150, v150
	v_max_f32_e32 v150, v150, v151
	v_cmp_lt_f32_e32 vcc, s77, v150
	s_cbranch_vccz .LBB0_589
	v_max_f32_e32 v32, v150, v150
	v_max_f32_e32 v150, 0, v32
	v_exp_f32_e64 v151, -v150
	s_and_saveexec_b64 s[4:5], s[2:3]
	ds_write_b32 v158, v151 offset:6144
	s_or_b64 exec, exec, s[4:5]
	ds_read_b128 v[164:167], v155 offset:6144
	ds_read_b128 v[168:171], v155 offset:6176
	ds_read_b128 v[172:175], v155 offset:6208
	ds_read_b128 v[176:179], v155 offset:6240
	v_add_f32_e32 v161, v161, v150
	v_xor_b32_e32 v32, 0x80000000, v161
	v_pk_add_f32 v[48:49], v[48:49], v[150:151] op_sel_hi:[1,0] neg_lo:[0,1] neg_hi:[0,1]
	v_pk_add_f32 v[64:65], v[64:65], v[150:151] op_sel_hi:[1,0] neg_lo:[0,1] neg_hi:[0,1]
	v_pk_add_f32 v[50:51], v[50:51], v[150:151] op_sel_hi:[1,0] neg_lo:[0,1] neg_hi:[0,1]
	v_pk_add_f32 v[66:67], v[66:67], v[150:151] op_sel_hi:[1,0] neg_lo:[0,1] neg_hi:[0,1]
	v_pk_add_f32 v[52:53], v[52:53], v[150:151] op_sel_hi:[1,0] neg_lo:[0,1] neg_hi:[0,1]
	v_pk_add_f32 v[68:69], v[68:69], v[150:151] op_sel_hi:[1,0] neg_lo:[0,1] neg_hi:[0,1]
	v_pk_add_f32 v[54:55], v[54:55], v[150:151] op_sel_hi:[1,0] neg_lo:[0,1] neg_hi:[0,1]
	v_pk_add_f32 v[70:71], v[70:71], v[150:151] op_sel_hi:[1,0] neg_lo:[0,1] neg_hi:[0,1]
	v_pk_add_f32 v[56:57], v[56:57], v[150:151] op_sel_hi:[1,0] neg_lo:[0,1] neg_hi:[0,1]
	v_pk_add_f32 v[72:73], v[72:73], v[150:151] op_sel_hi:[1,0] neg_lo:[0,1] neg_hi:[0,1]
	v_pk_add_f32 v[58:59], v[58:59], v[150:151] op_sel_hi:[1,0] neg_lo:[0,1] neg_hi:[0,1]
	v_pk_add_f32 v[74:75], v[74:75], v[150:151] op_sel_hi:[1,0] neg_lo:[0,1] neg_hi:[0,1]
	v_pk_add_f32 v[60:61], v[60:61], v[150:151] op_sel_hi:[1,0] neg_lo:[0,1] neg_hi:[0,1]
	v_pk_add_f32 v[76:77], v[76:77], v[150:151] op_sel_hi:[1,0] neg_lo:[0,1] neg_hi:[0,1]
	v_mov_b32_e32 v33, v32
	v_mov_b32_e32 v34, v32
	v_mov_b32_e32 v35, v32
	v_mov_b32_e32 v36, v32
	v_mov_b32_e32 v37, v32
	v_mov_b32_e32 v38, v32
	v_mov_b32_e32 v39, v32
	v_mov_b32_e32 v40, v32
	v_mov_b32_e32 v41, v32
	v_mov_b32_e32 v42, v32
	v_mov_b32_e32 v43, v32
	v_mov_b32_e32 v44, v32
	v_mov_b32_e32 v45, v32
	v_mov_b32_e32 v46, v32
	v_mov_b32_e32 v47, v32
	v_pk_add_f32 v[62:63], v[62:63], v[150:151] op_sel_hi:[1,0] neg_lo:[0,1] neg_hi:[0,1]
	v_pk_add_f32 v[78:79], v[78:79], v[150:151] op_sel_hi:[1,0] neg_lo:[0,1] neg_hi:[0,1]
	v_mul_f32_e32 v160, v160, v151
	s_waitcnt lgkmcnt(0)
	v_pk_mul_f32 v[30:31], v[30:31], v[178:179]
	v_pk_mul_f32 v[26:27], v[26:27], v[174:175]
	v_pk_mul_f32 v[22:23], v[22:23], v[170:171]
	v_pk_mul_f32 v[18:19], v[18:19], v[166:167]
	v_pk_mul_f32 v[28:29], v[28:29], v[176:177]
	v_pk_mul_f32 v[24:25], v[24:25], v[172:173]
	v_pk_mul_f32 v[20:21], v[20:21], v[168:169]
	v_pk_mul_f32 v[16:17], v[16:17], v[164:165]
	v_pk_mul_f32 v[14:15], v[14:15], v[178:179]
	v_pk_mul_f32 v[10:11], v[10:11], v[174:175]
	v_pk_mul_f32 v[6:7], v[6:7], v[170:171]
	v_pk_mul_f32 v[2:3], v[2:3], v[166:167]
	v_pk_mul_f32 v[12:13], v[12:13], v[176:177]
	v_pk_mul_f32 v[8:9], v[8:9], v[172:173]
	v_pk_mul_f32 v[4:5], v[4:5], v[168:169]
	v_pk_mul_f32 v[0:1], v[0:1], v[164:165]
; __device__ __forceinline__ s16x4 vtr(const LAS unsigned char* p) { return __builtin_bit_cast(s16x4, __builtin_amdgcn_ds_read_tr16_b64_v4i16((LAS v4i16_t*)p)); }
; template <int DQK, int DV, bool HAS_BIAS>
; __device__ __forceinline__ void attn_tile(AttnState<DQK, DV>& st, const LAS unsigned char* Kt, const LAS unsigned char* Vt, int bias_mode, const LAS float* tab, int rel0, int nkeys, bool first, LAS float* wsf, int lane) {
;     ...
;     float sum0 = 0.f, sum1 = 0.f;
; #pragma unroll
;     for (int r = 0; r < 16; ++r) { p0[r] = __builtin_amdgcn_exp2f(p0[r]); p1[r] = __builtin_amdgcn_exp2f(p1[r]); sum0 += p0[r]; sum1 += p1[r]; }
;     st.l += sum0 + sum1;
;     bf16x8 pf[4];
;     pf[0] = pack8(p0[0], p0[1], p0[2], p0[3], p0[4], p0[5], p0[6], p0[7]);
;     pf[1] = pack8(p0[8], p0[9], p0[10], p0[11], p0[12], p0[13], p0[14], p0[15]);
;     pf[2] = pack8(p1[0], p1[1], p1[2], p1[3], p1[4], p1[5], p1[6], p1[7]);
;     pf[3] = pack8(p1[8], p1[9], p1[10], p1[11], p1[12], p1[13], p1[14], p1[15]);
;     __builtin_amdgcn_sched_barrier(0);
; #pragma unroll
;     for (int db = 0; db < NDB; ++db) {
;         if (db + 1 < NDB) {
; #pragma unroll
;             for (int s4 = 0; s4 < 4; ++s4) { vlo[(db + 1) & 1][s4] = vtr(vp + (16 * s4) * PV + (db + 1) * 64); vhi[(db + 1) & 1][s4] = vtr(vp + (16 * s4 + 8) * PV + (db + 1) * 64); }
;         }
; #pragma unroll
;         for (int s4 = 0; s4 < 4; ++s4) {
;             const s16x4 lo = vlo[db & 1][s4], h4 = vhi[db & 1][s4];
;             const bf16x8 vb = {lo[0], lo[1], lo[2], lo[3], h4[0], h4[1], h4[2], h4[3]};
;             st.o[db] = __builtin_amdgcn_mfma_f32_32x32x16_bf16(pf[s4], vb, st.o[db], 0, 0, 0);
;         }
;         __builtin_amdgcn_sched_barrier(0);
;     }
.LBB0_589:
	v_exp_f32_e32 v164, v48
	v_exp_f32_e32 v165, v49
	v_add_f32_e32 v182, 0, v164
	v_exp_f32_e32 v166, v50
	v_add_f32_e32 v182, v165, v182
	v_exp_f32_e32 v167, v51
	v_add_f32_e32 v182, v166, v182
	v_exp_f32_e32 v168, v52
	v_add_f32_e32 v182, v167, v182
	v_exp_f32_e32 v169, v53
	v_add_f32_e32 v182, v168, v182
	v_exp_f32_e32 v170, v54
	v_add_f32_e32 v182, v169, v182
	v_exp_f32_e32 v171, v55
	v_add_f32_e32 v182, v170, v182
	v_cvt_pk_bf16_f32 v48, v164, v165
	v_add_f32_e32 v182, v171, v182
	v_cvt_pk_bf16_f32 v49, v166, v167
	v_cvt_pk_bf16_f32 v50, v168, v169
	v_cvt_pk_bf16_f32 v51, v170, v171
	s_nop 1
	s_waitcnt lgkmcnt(4)
	v_mfma_f32_32x32x16_bf16 v[16:31], v[48:51], v[128:131], v[16:31]
	v_exp_f32_e32 v172, v56
	v_exp_f32_e32 v173, v57
	v_add_f32_e32 v182, v172, v182
	v_exp_f32_e32 v174, v58
	v_add_f32_e32 v182, v173, v182
	v_exp_f32_e32 v175, v59
	v_add_f32_e32 v182, v174, v182
	v_exp_f32_e32 v176, v60
	v_add_f32_e32 v182, v175, v182
	v_exp_f32_e32 v177, v61
	v_mfma_f32_32x32x16_bf16 v[0:15], v[48:51], v[132:135], v[0:15]
	v_add_f32_e32 v182, v176, v182
	v_exp_f32_e32 v178, v62
	v_add_f32_e32 v182, v177, v182
	v_exp_f32_e32 v179, v63
	v_add_f32_e32 v182, v178, v182
	v_cvt_pk_bf16_f32 v52, v172, v173
	v_add_f32_e32 v182, v179, v182
	v_cvt_pk_bf16_f32 v53, v174, v175
	v_cvt_pk_bf16_f32 v54, v176, v177
	v_cvt_pk_bf16_f32 v55, v178, v179
	ds_read_b64_tr_b16 v[128:129], v163 offset:53248
	ds_read_b64_tr_b16 v[130:131], v163 offset:54784
	ds_read_b64_tr_b16 v[132:133], v163 offset:53312
	ds_read_b64_tr_b16 v[134:135], v163 offset:54848
	s_waitcnt lgkmcnt(4)
	v_mfma_f32_32x32x16_bf16 v[16:31], v[52:55], v[136:139], v[16:31]
	v_exp_f32_e32 v164, v64
	v_exp_f32_e32 v165, v65
	v_add_f32_e32 v183, 0, v164
	v_exp_f32_e32 v166, v66
	v_add_f32_e32 v183, v165, v183
	v_exp_f32_e32 v167, v67
	v_add_f32_e32 v183, v166, v183
	v_exp_f32_e32 v168, v68
	v_add_f32_e32 v183, v167, v183
	v_exp_f32_e32 v169, v69
	v_mfma_f32_32x32x16_bf16 v[0:15], v[52:55], v[140:143], v[0:15]
	v_add_f32_e32 v183, v168, v183
	v_exp_f32_e32 v170, v70
	v_add_f32_e32 v183, v169, v183
	v_exp_f32_e32 v171, v71
	v_add_f32_e32 v183, v170, v183
	v_cvt_pk_bf16_f32 v56, v164, v165
	v_add_f32_e32 v183, v171, v183
	v_cvt_pk_bf16_f32 v57, v166, v167
	v_cvt_pk_bf16_f32 v58, v168, v169
	v_cvt_pk_bf16_f32 v59, v170, v171
	ds_read_b64_tr_b16 v[136:137], v163 offset:56320
	ds_read_b64_tr_b16 v[138:139], v163 offset:57856
	ds_read_b64_tr_b16 v[140:141], v163 offset:56384
	ds_read_b64_tr_b16 v[142:143], v163 offset:57920
	s_waitcnt lgkmcnt(4)
	v_mfma_f32_32x32x16_bf16 v[16:31], v[56:59], v[128:131], v[16:31]
	v_exp_f32_e32 v172, v72
	v_exp_f32_e32 v173, v73
	v_add_f32_e32 v183, v172, v183
	v_exp_f32_e32 v174, v74
	v_add_f32_e32 v183, v173, v183
	v_exp_f32_e32 v175, v75
	v_add_f32_e32 v183, v174, v183
	v_exp_f32_e32 v176, v76
	v_add_f32_e32 v183, v175, v183
	v_exp_f32_e32 v177, v77
	v_mfma_f32_32x32x16_bf16 v[0:15], v[56:59], v[132:135], v[0:15]
	v_add_f32_e32 v183, v176, v183
	v_exp_f32_e32 v178, v78
	v_add_f32_e32 v183, v177, v183
	v_exp_f32_e32 v179, v79
	v_add_f32_e32 v183, v178, v183
	v_cvt_pk_bf16_f32 v60, v172, v173
	v_add_f32_e32 v183, v179, v183
	v_cvt_pk_bf16_f32 v61, v174, v175
	v_cvt_pk_bf16_f32 v62, v176, v177
	v_cvt_pk_bf16_f32 v63, v178, v179
	s_waitcnt lgkmcnt(0)
	v_mfma_f32_32x32x16_bf16 v[16:31], v[60:63], v[136:139], v[16:31]
	v_add_f32_e32 v182, v183, v182
	v_mfma_f32_32x32x16_bf16 v[0:15], v[60:63], v[140:143], v[0:15]
	v_add_f32_e32 v160, v160, v182
	s_andn2_b64 vcc, exec, s[36:37]
	s_cbranch_vccnz .LBB0_593

; __device__ __forceinline__ s16x4 vtr(const LAS unsigned char* p) { return __builtin_bit_cast(s16x4, __builtin_amdgcn_ds_read_tr16_b64_v4i16((LAS v4i16_t*)p)); }
; #define ATT_STORE(S, bufp) do { *(LAS u32x4*)((bufp) + kdst) = rk##S; if (!DIFF && tid < 256) *(LAS u32x4*)((bufp) + k2dst) = rk2##S; \
;         *(LAS u32x4*)((bufp) + vdst) = rv0##S; if (DIFF) *(LAS u32x4*)((bufp) + vdst + 32 * PV) = rv1##S; } while (0)
; template <int DQK, int DV, bool HAS_BIAS>
; __device__ __forceinline__ void attn_tile(AttnState<DQK, DV>& st, const LAS unsigned char* Kt, const LAS unsigned char* Vt, int bias_mode, const LAS float* tab, int rel0, int nkeys, bool first, LAS float* wsf, int lane) {
;     ...
;     float sum0 = 0.f, sum1 = 0.f;
; #pragma unroll
;     for (int r = 0; r < 16; ++r) { p0[r] = __builtin_amdgcn_exp2f(p0[r]); p1[r] = __builtin_amdgcn_exp2f(p1[r]); sum0 += p0[r]; sum1 += p1[r]; }
;     st.l += sum0 + sum1;
;     bf16x8 pf[4];
;     pf[0] = pack8(p0[0], p0[1], p0[2], p0[3], p0[4], p0[5], p0[6], p0[7]);
;     pf[1] = pack8(p0[8], p0[9], p0[10], p0[11], p0[12], p0[13], p0[14], p0[15]);
;     pf[2] = pack8(p1[0], p1[1], p1[2], p1[3], p1[4], p1[5], p1[6], p1[7]);
;     pf[3] = pack8(p1[8], p1[9], p1[10], p1[11], p1[12], p1[13], p1[14], p1[15]);
;     __builtin_amdgcn_sched_barrier(0);
; #pragma unroll
;     for (int db = 0; db < NDB; ++db) {
;         if (db + 1 < NDB) {
; #pragma unroll
;             for (int s4 = 0; s4 < 4; ++s4) { vlo[(db + 1) & 1][s4] = vtr(vp + (16 * s4) * PV + (db + 1) * 64); vhi[(db + 1) & 1][s4] = vtr(vp + (16 * s4 + 8) * PV + (db + 1) * 64); }
;         }
; #pragma unroll
;         for (int s4 = 0; s4 < 4; ++s4) {
;             const s16x4 lo = vlo[db & 1][s4], h4 = vhi[db & 1][s4];
;             const bf16x8 vb = {lo[0], lo[1], lo[2], lo[3], h4[0], h4[1], h4[2], h4[3]};
;             st.o[db] = __builtin_amdgcn_mfma_f32_32x32x16_bf16(pf[s4], vb, st.o[db], 0, 0, 0);
;         }
;         __builtin_amdgcn_sched_barrier(0);
;     }
; template <bool DIFF>
; __device__ __forceinline__ void attn_unit_coop(const Grp& G, int b, int h, int qb, int n, LAS unsigned char* lds, const int tid_in) {
;     ...
;             ATT_STORE(A, b1);
.LBB0_601:
	v_exp_f32_e32 v164, v48
	v_exp_f32_e32 v165, v49
	v_add_f32_e32 v182, 0, v164
	v_exp_f32_e32 v166, v50
	v_add_f32_e32 v182, v165, v182
	v_exp_f32_e32 v167, v51
	v_add_f32_e32 v182, v166, v182
	v_exp_f32_e32 v168, v52
	v_add_f32_e32 v182, v167, v182
	v_exp_f32_e32 v169, v53
	v_add_f32_e32 v182, v168, v182
	v_exp_f32_e32 v170, v54
	v_add_f32_e32 v182, v169, v182
	v_exp_f32_e32 v171, v55
	v_add_f32_e32 v182, v170, v182
	v_cvt_pk_bf16_f32 v48, v164, v165
	v_add_f32_e32 v182, v171, v182
	v_cvt_pk_bf16_f32 v49, v166, v167
	v_cvt_pk_bf16_f32 v50, v168, v169
	v_cvt_pk_bf16_f32 v51, v170, v171
	s_nop 1
	s_waitcnt lgkmcnt(4)
	v_mfma_f32_32x32x16_bf16 v[16:31], v[48:51], v[128:131], v[16:31]
	v_exp_f32_e32 v172, v56
	v_exp_f32_e32 v173, v57
	v_add_f32_e32 v182, v172, v182
	v_exp_f32_e32 v174, v58
	v_add_f32_e32 v182, v173, v182
	v_exp_f32_e32 v175, v59
	v_add_f32_e32 v182, v174, v182
	v_exp_f32_e32 v176, v60
	v_add_f32_e32 v182, v175, v182
	v_exp_f32_e32 v177, v61
	v_mfma_f32_32x32x16_bf16 v[0:15], v[48:51], v[132:135], v[0:15]
	v_add_f32_e32 v182, v176, v182
	v_exp_f32_e32 v178, v62
	v_add_f32_e32 v182, v177, v182
	v_exp_f32_e32 v179, v63
	v_add_f32_e32 v182, v178, v182
	v_cvt_pk_bf16_f32 v52, v172, v173
	v_add_f32_e32 v182, v179, v182
	v_cvt_pk_bf16_f32 v53, v174, v175
	v_cvt_pk_bf16_f32 v54, v176, v177
	v_cvt_pk_bf16_f32 v55, v178, v179
	ds_read_b64_tr_b16 v[128:129], v163 offset:27648
	ds_read_b64_tr_b16 v[130:131], v163 offset:29184
	ds_read_b64_tr_b16 v[132:133], v163 offset:27712
	ds_read_b64_tr_b16 v[134:135], v163 offset:29248
	s_waitcnt lgkmcnt(4)
	v_mfma_f32_32x32x16_bf16 v[16:31], v[52:55], v[136:139], v[16:31]
	v_exp_f32_e32 v164, v64
	v_exp_f32_e32 v165, v65
	v_add_f32_e32 v183, 0, v164
	v_exp_f32_e32 v166, v66
	v_add_f32_e32 v183, v165, v183
	v_exp_f32_e32 v167, v67
	v_add_f32_e32 v183, v166, v183
	v_exp_f32_e32 v168, v68
	v_add_f32_e32 v183, v167, v183
	v_exp_f32_e32 v169, v69
	v_mfma_f32_32x32x16_bf16 v[0:15], v[52:55], v[140:143], v[0:15]
	v_add_f32_e32 v183, v168, v183
	v_exp_f32_e32 v170, v70
	v_add_f32_e32 v183, v169, v183
	v_exp_f32_e32 v171, v71
	v_add_f32_e32 v183, v170, v183
	v_cvt_pk_bf16_f32 v56, v164, v165
	v_add_f32_e32 v183, v171, v183
	v_cvt_pk_bf16_f32 v57, v166, v167
	v_cvt_pk_bf16_f32 v58, v168, v169
	v_cvt_pk_bf16_f32 v59, v170, v171
	ds_read_b64_tr_b16 v[136:137], v163 offset:30720
	ds_read_b64_tr_b16 v[138:139], v163 offset:32256
	ds_read_b64_tr_b16 v[140:141], v163 offset:30784
	ds_read_b64_tr_b16 v[142:143], v163 offset:32320
	s_waitcnt lgkmcnt(4)
	v_mfma_f32_32x32x16_bf16 v[16:31], v[56:59], v[128:131], v[16:31]
	v_exp_f32_e32 v172, v72
	v_exp_f32_e32 v173, v73
	v_add_f32_e32 v183, v172, v183
	v_exp_f32_e32 v174, v74
	v_add_f32_e32 v183, v173, v183
	v_exp_f32_e32 v175, v75
	v_add_f32_e32 v183, v174, v183
	v_exp_f32_e32 v176, v76
	v_add_f32_e32 v183, v175, v183
	v_exp_f32_e32 v177, v77
	v_mfma_f32_32x32x16_bf16 v[0:15], v[56:59], v[132:135], v[0:15]
	v_add_f32_e32 v183, v176, v183
	v_exp_f32_e32 v178, v78
	v_add_f32_e32 v183, v177, v183
	v_exp_f32_e32 v179, v79
	v_add_f32_e32 v183, v178, v183
	v_cvt_pk_bf16_f32 v60, v172, v173
	v_add_f32_e32 v183, v179, v183
	v_cvt_pk_bf16_f32 v61, v174, v175
	v_cvt_pk_bf16_f32 v62, v176, v177
	v_cvt_pk_bf16_f32 v63, v178, v179
	s_waitcnt lgkmcnt(0)
	v_mfma_f32_32x32x16_bf16 v[16:31], v[60:63], v[136:139], v[16:31]
	v_add_f32_e32 v182, v183, v182
	v_mfma_f32_32x32x16_bf16 v[0:15], v[60:63], v[140:143], v[0:15]
	v_add_f32_e32 v160, v160, v182
	s_waitcnt vmcnt(1)
	ds_write_b128 v156, v[108:111] offset:33792
	s_and_saveexec_b64 s[4:5], s[0:1]
	s_cbranch_execnz .LBB0_573
	s_branch .LBB0_574
